# panel-norm epilogues: four per-owner row partial loads issued together (one wait) instead of load-wait-add chain
# baseline (speedup 1.0000x reference)
;     __device__ __forceinline__ void fused(Acc& acc, const pg8::Unit& u, int wr, int wc, int fr, int fq, LAS unsigned char* lds, int wid, int lane) const {
;     ...
;         if (lane < 32) { float tot = 0.f;
; #pragma unroll
;             for (int t4 = 0; t4 < 4; ++t4) tot += __uint_as_float(__hip_atomic_load(slots + (size_t)(tile0 + row) * 4 + t4, __ATOMIC_RELAXED, __HIP_MEMORY_SCOPE_AGENT));
;             S[row] = __builtin_amdgcn_rsqf(tot * (1.f / DM) + EPSV); }
.LBB0_972:
	s_waitcnt vmcnt(0) lgkmcnt(0)
	s_barrier
	s_and_saveexec_b64 s[4:5], s[0:1]
	s_cbranch_execz .LBB0_974
	v_lshl_add_u64 v[16:17], v[16:17], 4, s[22:23]
	global_load_dword v19, v[16:17], off sc1
	global_load_dword v20, v[16:17], off offset:4 sc1
	global_load_dword v250, v[16:17], off offset:8 sc1
	global_load_dword v16, v[16:17], off offset:12 sc1
	v_lshl_add_u32 v17, v18, 2, 0
	s_waitcnt vmcnt(0)
	v_add_f32_e32 v19, 0, v19
	v_add_f32_e32 v19, v19, v20
	v_add_f32_e32 v19, v19, v250
	v_add_f32_e32 v16, v19, v16
	v_fmamk_f32 v16, v16, 0x3a800000, v193
	v_rsq_f32_e32 v16, v16
	ds_write_b32 v17, v16 offset:4096

;     __device__ __forceinline__ void fused(Acc& acc, const pg8::Unit& u, int wr, int wc, int fr, int fq, LAS unsigned char* lds, int wid, int lane) const {
;     ...
;         if (lane < 32) { float tot = 0.f;
; #pragma unroll
;             for (int t4 = 0; t4 < 4; ++t4) tot += __uint_as_float(__hip_atomic_load(slots + (size_t)(tile0 + row) * 4 + t4, __ATOMIC_RELAXED, __HIP_MEMORY_SCOPE_AGENT));
;             S[row] = __builtin_amdgcn_rsqf(tot * (1.f / DM) + EPSV); }
.LBB0_1076:
	s_waitcnt vmcnt(0) lgkmcnt(0)
	s_barrier
	s_and_saveexec_b64 s[12:13], s[6:7]
	s_cbranch_execz .LBB0_1078
	v_readlane_b32 s24, v254, 25
	v_readlane_b32 s25, v254, 26
	s_nop 1
	v_lshl_add_u64 v[16:17], v[16:17], 4, s[24:25]
	global_load_dword v18, v[16:17], off sc1
	global_load_dword v19, v[16:17], off offset:4 sc1
	v_readlane_b32 s24, v255, 21
	global_load_dword v250, v[16:17], off offset:8 sc1
	global_load_dword v16, v[16:17], off offset:12 sc1
	v_lshl_add_u32 v17, v184, 2, s24
	s_waitcnt vmcnt(0)
	v_add_f32_e32 v18, 0, v18
	v_add_f32_e32 v18, v18, v19
	v_add_f32_e32 v18, v18, v250
	v_add_f32_e32 v16, v18, v16
	v_fmamk_f32 v16, v16, 0x3a800000, v193
	v_rsq_f32_e32 v16, v16
	ds_write_b32 v17, v16

;     __device__ __forceinline__ void fused(Acc& acc, const pg8::Unit& u, int wr, int wc, int fr, int fq, LAS unsigned char* lds, int wid, int lane) const {
;     ...
;         if (lane < 32) { float tot = 0.f;
; #pragma unroll
;             for (int t4 = 0; t4 < 4; ++t4) tot += __uint_as_float(__hip_atomic_load(slots + (size_t)(tile0 + row) * 4 + t4, __ATOMIC_RELAXED, __HIP_MEMORY_SCOPE_AGENT));
;             S[row] = __builtin_amdgcn_rsqf(tot * (1.f / DM) + EPSV); }
.LBB0_1334:
	s_waitcnt vmcnt(0) lgkmcnt(0)
	s_barrier
	s_and_saveexec_b64 s[6:7], s[0:1]
	s_cbranch_execz .LBB0_1336
	v_lshl_add_u64 v[0:1], v[0:1], 4, s[18:19]
	global_load_dword v3, v[0:1], off sc1
	global_load_dword v4, v[0:1], off offset:4 sc1
	global_load_dword v250, v[0:1], off offset:8 sc1
	global_load_dword v0, v[0:1], off offset:12 sc1
	v_lshl_add_u32 v1, v2, 2, 0
	s_waitcnt vmcnt(0)
	v_add_f32_e32 v3, 0, v3
	v_add_f32_e32 v3, v3, v4
	v_add_f32_e32 v3, v3, v250
	v_add_f32_e32 v0, v3, v0
	v_fmamk_f32 v0, v0, 0x3a800000, v193
	v_rsq_f32_e32 v0, v0
	ds_write_b32 v1, v0 offset:4096

;     __device__ __forceinline__ void fused(Acc& acc, const pg8::Unit& u, int wr, int wc, int fr, int fq, LAS unsigned char* lds, int wid, int lane) const {
;     ...
;         if (lane < 32) { float tot = 0.f;
; #pragma unroll
;             for (int t4 = 0; t4 < 4; ++t4) tot += __uint_as_float(__hip_atomic_load(slots + (size_t)(tile0 + row) * 4 + t4, __ATOMIC_RELAXED, __HIP_MEMORY_SCOPE_AGENT));
;             S[row] = __builtin_amdgcn_rsqf(tot * (1.f / DM) + EPSV); }
.LBB0_1438:
	s_waitcnt vmcnt(0) lgkmcnt(0)
	s_barrier
	s_and_saveexec_b64 s[12:13], s[6:7]
	s_cbranch_execz .LBB0_1440
	v_readlane_b32 s24, v254, 38
	v_readlane_b32 s25, v254, 39
	s_nop 1
	v_lshl_add_u64 v[16:17], v[16:17], 4, s[24:25]
	global_load_dword v18, v[16:17], off sc1
	global_load_dword v19, v[16:17], off offset:4 sc1
	v_readlane_b32 s24, v255, 21
	global_load_dword v250, v[16:17], off offset:8 sc1
	global_load_dword v16, v[16:17], off offset:12 sc1
	v_lshl_add_u32 v17, v180, 2, s24
	s_waitcnt vmcnt(0)
	v_add_f32_e32 v18, 0, v18
	v_add_f32_e32 v18, v18, v19
	v_add_f32_e32 v18, v18, v250
	v_add_f32_e32 v16, v18, v16
	v_fmamk_f32 v16, v16, 0x3a800000, v193
	v_rsq_f32_e32 v16, v16
	ds_write_b32 v17, v16
